# GEMM epilogue: 8 rowscale loads issued together, 7 per-block load+vmcnt(0) drains removed (plus scan2 tail / combine edits)
# speedup vs baseline: 1.0294x; 1.0284x over previous
;     __device__ __forceinline__ void operator()(const f32x4 (&acc)[2][2][4][2], const Unit& u, int wr, int wc, int fr, int fq) const {
;     ...
;         for (int ai = 0; ai < 2; ++ai)
; #pragma unroll
;             for (int m = 0; m < 4; ++m) {
;                 const int row = u.pm * BM + ai * HALF + wr * 64 + m * 16 + fr;
;                 const float rsc = P.rowscale ? P.scal * P.rowscale[row] : P.scal;
.LBB0_515:
	v_lshl_add_u32 v144, s70, 8, v190
	s_cmp_lg_u64 s[16:17], 0
	v_ashrrev_i32_e32 v145, 31, v144
	s_cselect_b64 s[66:67], -1, 0
	s_cmp_eq_u64 s[16:17], 0
	v_mov_b32_e32 v152, s44
	v_lshl_add_u64 v[148:149], v[144:145], 2, s[16:17]
	s_cbranch_scc1 .LBB0_517
	global_load_dword v146, v[148:149], off
	global_load_dword v202, v[148:149], off offset:64
	global_load_dword v203, v[148:149], off offset:128
	global_load_dword v204, v[148:149], off offset:192
	global_load_dword v205, v[148:149], off offset:512
	global_load_dword v206, v[148:149], off offset:576
	global_load_dword v207, v[148:149], off offset:640
	global_load_dword v208, v[148:149], off offset:704
	s_waitcnt vmcnt(0)
	v_mul_f32_e32 v152, s44, v146

;     __device__ __forceinline__ void operator()(const f32x4 (&acc)[2][2][4][2], const Unit& u, int wr, int wc, int fr, int fq) const {
;     ...
;             for (int m = 0; m < 4; ++m) {
;                 const int row = u.pm * BM + ai * HALF + wr * 64 + m * 16 + fr;
;                 const float rsc = P.rowscale ? P.scal * P.rowscale[row] : P.scal;
.LBB0_542:
	v_cndmask_b32_e64 v118, 0, 1, s[66:67]
	v_cmp_ne_u32_e64 s[26:27], 1, v118
	s_andn2_b64 vcc, exec, s[66:67]
	v_mov_b32_e32 v118, s44
	s_cbranch_vccnz .LBB0_544
	s_nop 0
	v_mul_f32_e32 v118, s44, v202

;     __device__ __forceinline__ void operator()(const f32x4 (&acc)[2][2][4][2], const Unit& u, int wr, int wc, int fr, int fq) const {
;     ...
;             for (int m = 0; m < 4; ++m) {
;                 const int row = u.pm * BM + ai * HALF + wr * 64 + m * 16 + fr;
;                 const float rsc = P.rowscale ? P.scal * P.rowscale[row] : P.scal;
.LBB0_564:
	s_and_b64 vcc, exec, s[26:27]
	v_mov_b32_e32 v100, s44
	s_cbranch_vccnz .LBB0_566
	s_nop 0
	v_mul_f32_e32 v100, s44, v203

;     __device__ __forceinline__ void operator()(const f32x4 (&acc)[2][2][4][2], const Unit& u, int wr, int wc, int fr, int fq) const {
;     ...
;             for (int m = 0; m < 4; ++m) {
;                 const int row = u.pm * BM + ai * HALF + wr * 64 + m * 16 + fr;
;                 const float rsc = P.rowscale ? P.scal * P.rowscale[row] : P.scal;
.LBB0_586:
	s_and_b64 vcc, exec, s[26:27]
	v_mov_b32_e32 v84, s44
	s_cbranch_vccnz .LBB0_588
	s_nop 0
	v_mul_f32_e32 v84, s44, v204

;     __device__ __forceinline__ void operator()(const f32x4 (&acc)[2][2][4][2], const Unit& u, int wr, int wc, int fr, int fq) const {
;     ...
;             for (int m = 0; m < 4; ++m) {
;                 const int row = u.pm * BM + ai * HALF + wr * 64 + m * 16 + fr;
;                 const float rsc = P.rowscale ? P.scal * P.rowscale[row] : P.scal;
.LBB0_608:
	s_and_b64 vcc, exec, s[26:27]
	v_mov_b32_e32 v68, s44
	s_cbranch_vccnz .LBB0_610
	s_nop 0
	v_mul_f32_e32 v68, s44, v205

;     __device__ __forceinline__ void operator()(const f32x4 (&acc)[2][2][4][2], const Unit& u, int wr, int wc, int fr, int fq) const {
;     ...
;             for (int m = 0; m < 4; ++m) {
;                 const int row = u.pm * BM + ai * HALF + wr * 64 + m * 16 + fr;
;                 const float rsc = P.rowscale ? P.scal * P.rowscale[row] : P.scal;
.LBB0_630:
	s_and_b64 vcc, exec, s[26:27]
	v_mov_b32_e32 v52, s44
	s_cbranch_vccnz .LBB0_632
	s_nop 0
	v_mul_f32_e32 v52, s44, v206

;     __device__ __forceinline__ void operator()(const f32x4 (&acc)[2][2][4][2], const Unit& u, int wr, int wc, int fr, int fq) const {
;     ...
;             for (int m = 0; m < 4; ++m) {
;                 const int row = u.pm * BM + ai * HALF + wr * 64 + m * 16 + fr;
;                 const float rsc = P.rowscale ? P.scal * P.rowscale[row] : P.scal;
.LBB0_652:
	s_and_b64 vcc, exec, s[26:27]
	v_mov_b32_e32 v36, s44
	s_cbranch_vccnz .LBB0_654
	s_nop 0
	v_mul_f32_e32 v36, s44, v207

;     __device__ __forceinline__ void operator()(const f32x4 (&acc)[2][2][4][2], const Unit& u, int wr, int wc, int fr, int fq) const {
;     ...
;             for (int m = 0; m < 4; ++m) {
;                 const int row = u.pm * BM + ai * HALF + wr * 64 + m * 16 + fr;
;                 const float rsc = P.rowscale ? P.scal * P.rowscale[row] : P.scal;
.LBB0_674:
	s_and_b64 vcc, exec, s[26:27]
	v_mov_b32_e32 v20, s44
	s_cbranch_vccnz .LBB0_676
	s_nop 0
	v_mul_f32_e32 v20, s44, v208
